# GEMM phase prologues: K-tile 1's six staging loads issued before the first wait (one memory round trip instead of two before the first MFMA)
# speedup vs baseline: 1.0037x; 1.0037x over previous
; #define PG8_STAGE(bufoff, gbase, voff) do { _Pragma("unroll") for (int _i = 0; _i < 2; ++_i) \
;         __builtin_amdgcn_global_load_lds((const unsigned*)((const char*)(gbase) + (voff)[_i]), (PG8_LAS unsigned*)(lds + (bufoff) + ldsw + _i * 8192), 16, 0, 0); } while (0)
; #define PG8_WAIT_V(n) asm volatile("s_waitcnt vmcnt(" #n ")" ::: "memory")
; #define PG8_BAR __builtin_amdgcn_s_barrier()
; template <class Epi, class Sched, bool ALIGN_EPI = false, bool SP2 = false>
; __device__ __forceinline__ void gemm_phase(PG8_LAS unsigned char* lds, const Gemm g, const Sched& S, const Epi& E) {
;     ...
;     if constexpr (SP2) {
;         PG8_STAGE(PG8_SB(0, 0), cB, voffB); PG8_STAGE(PG8_SB(0, 1), cB + hstep, voffB); PG8_STAGE(PG8_SA(0, 0), cA, voffA); PG8_STAGE(PG8_SA(0, 1), cA + hstep, voffA);
;         if (wr == 1) PG8_BAR;
;         PG8_WAIT_V(2); PG8_BAR;
;         PG8_STAGE(PG8_SB(1, 0), cB + kstep, voffB); PG8_STAGE(PG8_SA(1, 0), cA + kstep, voffA); PG8_STAGE(PG8_SB(1, 1), cB + hstep + kstep, voffB);
;         PG8_WAIT_V(6); PG8_BAR;
;     } else {
.LBB0_147:
	v_readlane_b32 s10, v255, 44
	v_readlane_b32 s11, v255, 45
	s_lshl_b32 s60, s10, 6
	s_lshl_b32 s10, s10, 11
	s_mov_b32 s11, s61
	s_lshl_b64 s[10:11], s[10:11], 2
	s_add_u32 s10, s52, s10
	s_addc_u32 s11, s53, s11
	s_and_b32 s73, s5, 3
	s_add_i32 m0, s69, 0x18000
	v_lshl_add_u64 v[6:7], v[6:7], 0, s[30:31]
	s_lshl_b32 s76, s14, 6
	s_lshl_b32 s7, s14, 13
	s_lshl_b32 s18, s73, 5
	s_lshl_b32 s16, s73, 12
	global_load_lds_dwordx4 v[6:7], off
	v_lshl_add_u64 v[4:5], v[4:5], 0, s[30:31]
	s_add_i32 m0, s69, 0x1a000
	s_add_i32 s77, s69, 0x8000
	s_add_i32 s78, s69, 0xa000
	global_load_lds_dwordx4 v[4:5], off
	v_lshl_add_u64 v[0:1], v[0:1], 0, s[30:31]
	s_mov_b32 m0, s77
	s_add_u32 s14, s42, 0x40080
	global_load_lds_dwordx4 v[0:1], off
	v_lshl_add_u64 v[0:1], v[2:3], 0, s[30:31]
	s_mov_b32 m0, s78
	s_addc_u32 s15, s43, 0
	global_load_lds_dwordx4 v[0:1], off
	s_add_i32 m0, s69, 0x1c000
	v_lshl_add_u64 v[0:1], s[14:15], 0, v[154:155]
	global_load_lds_dwordx4 v[0:1], off
	v_lshl_add_u64 v[0:1], s[14:15], 0, v[152:153]
	s_add_i32 m0, s69, 0x1e000
	v_and_b32_e32 v181, 15, v11
	global_load_lds_dwordx4 v[0:1], off
	s_waitcnt vmcnt(8)
	s_barrier
	v_bfe_u32 v1, v11, 4, 2
	v_lshlrev_b32_e32 v0, 4, v1
	v_lshlrev_b32_e32 v3, 2, v11
	v_lshlrev_b32_e32 v156, 3, v1
	v_lshl_or_b32 v2, v181, 6, v0
	v_and_b32_e32 v3, 32, v3
	v_bitop3_b32 v4, v2, s7, v3 bitop3:0xde
	v_bitop3_b32 v182, v2, s16, v3 bitop3:0xde
	v_or_b32_e32 v2, s18, v156
	v_and_or_b32 v3, s18, 32, v156
	v_or_b32_e32 v183, 0xffffe700, v2
	v_lshlrev_b32_e32 v2, 2, v1
	v_lshlrev_b32_e32 v184, 1, v3
	v_lshlrev_b32_e32 v1, 5, v1
	v_readlane_b32 s16, v254, 8
	v_lshl_add_u64 v[160:161], s[34:35], 0, v[184:185]
	v_lshl_or_b32 v184, v181, 7, v1
	v_mov_b32_e32 v1, v185
	v_readlane_b32 s17, v254, 9
	s_cmpk_lt_u32 s13, 0x100
	s_sext_i32_i16 s83, s12
	v_lshl_add_u64 v[164:165], s[16:17], 0, v[0:1]
	v_lshlrev_b32_e32 v0, 14, v12
	v_and_b32_e32 v0, 0xffff8000, v0
	v_lshl_add_u32 v0, v13, 11, v0
	v_and_b32_e32 v1, 1, v12
	v_lshl_or_b32 v0, v1, 6, v0
	v_lshl_add_u32 v166, v14, 1, v0
	v_lshlrev_b32_e32 v0, 14, v8
	v_and_b32_e32 v0, 0xffff8000, v0
	s_waitcnt vmcnt(6)
	s_cselect_b64 s[12:13], -1, 0
	s_cmp_gt_u32 s73, 1
	v_lshl_add_u32 v0, v9, 11, v0
	v_and_b32_e32 v1, 1, v8
	s_cselect_b64 s[14:15], -1, 0
	v_mov_b32_e32 v157, v185
	s_bfe_u32 s80, s5, 0x10001
	s_mov_b32 s5, s61
	v_lshl_or_b32 v0, v1, 6, v0
	s_add_i32 s79, s73, -2
	v_lshl_add_u64 v[158:159], s[66:67], 0, v[156:157]
	v_lshl_add_u64 v[162:163], s[40:41], 0, v[184:185]
	v_mov_b32_e32 v167, v185
	v_lshl_add_u32 v168, v10, 1, v0
	v_mov_b32_e32 v169, v185
	s_mov_b32 s81, 0
	v_add_u32_e32 v157, 0, v4
	s_lshl_b64 s[16:17], s[60:61], 2
	v_lshlrev_b32_e32 v190, 2, v2
	s_lshl_b32 s82, s18, 1
	v_mov_b64_e32 v[170:171], s[4:5]
	s_barrier
	s_branch .LBB0_150

; #define PG8_STAGE(bufoff, gbase, voff) do { _Pragma("unroll") for (int _i = 0; _i < 2; ++_i) \
;         __builtin_amdgcn_global_load_lds((const unsigned*)((const char*)(gbase) + (voff)[_i]), (PG8_LAS unsigned*)(lds + (bufoff) + ldsw + _i * 8192), 16, 0, 0); } while (0)
; #define PG8_WAIT_V(n) asm volatile("s_waitcnt vmcnt(" #n ")" ::: "memory")
; #define PG8_BAR __builtin_amdgcn_s_barrier()
; template <class Epi, class Sched, bool ALIGN_EPI = false, bool SP2 = false>
; __device__ __forceinline__ void gemm_phase(PG8_LAS unsigned char* lds, const Gemm g, const Sched& S, const Epi& E) {
;     ...
;     if constexpr (SP2) {
;         PG8_STAGE(PG8_SB(0, 0), cB, voffB); PG8_STAGE(PG8_SB(0, 1), cB + hstep, voffB); PG8_STAGE(PG8_SA(0, 0), cA, voffA); PG8_STAGE(PG8_SA(0, 1), cA + hstep, voffA);
;         if (wr == 1) PG8_BAR;
;         PG8_WAIT_V(2); PG8_BAR;
;         PG8_STAGE(PG8_SB(1, 0), cB + kstep, voffB); PG8_STAGE(PG8_SA(1, 0), cA + kstep, voffA); PG8_STAGE(PG8_SB(1, 1), cB + hstep + kstep, voffB);
;         PG8_WAIT_V(6); PG8_BAR;
;     } else {
.LBB0_364:
	v_lshrrev_b32_e32 v16, 1, v6
	v_and_b32_e32 v16, 24, v16
	v_and_b32_e32 v7, 15, v6
	v_lshlrev_b32_e32 v17, 1, v16
	v_lshlrev_b32_e32 v6, 2, v6
	s_lshl_b32 s7, s7, 5
	v_lshl_or_b32 v152, s14, 6, v7
	v_lshl_or_b32 v7, v7, 6, v17
	s_lshl_b32 s14, s14, 13
	v_and_b32_e32 v6, 32, v6
	s_and_b32 s7, s7, 0x60
	v_lshl_add_u64 v[8:9], s[36:37], 0, v[184:185]
	v_mov_b32_e32 v145, v185
	v_readlane_b32 s24, v255, 6
	v_bitop3_b32 v17, v7, s14, v6 bitop3:0xde
	s_lshl_b32 s14, s7, 7
	v_lshl_add_u64 v[10:11], s[36:37], 0, v[144:145]
	v_readlane_b32 s25, v255, 7
	v_bitop3_b32 v153, v7, s14, v6 bitop3:0xde
	s_add_i32 m0, s45, 0x18000
	v_lshl_add_u64 v[6:7], v[8:9], 0, s[30:31]
	v_lshl_add_u64 v[12:13], s[24:25], 0, v[184:185]
	global_load_lds_dwordx4 v[6:7], off
	v_lshl_add_u64 v[6:7], v[10:11], 0, s[30:31]
	s_add_i32 m0, s45, 0x1a000
	s_add_i32 s49, s45, 0x8000
	s_add_i32 s60, s45, 0xa000
	v_lshl_add_u64 v[14:15], s[24:25], 0, v[144:145]
	global_load_lds_dwordx4 v[6:7], off
	v_lshl_add_u64 v[6:7], v[12:13], 0, s[30:31]
	s_mov_b32 m0, s49
	s_add_u32 s14, s36, 0x40080
	global_load_lds_dwordx4 v[6:7], off
	v_lshl_add_u64 v[6:7], v[14:15], 0, s[30:31]
	s_mov_b32 m0, s60
	s_addc_u32 s15, s37, 0
	global_load_lds_dwordx4 v[6:7], off
	s_add_i32 m0, s45, 0x1c000
	v_lshl_add_u64 v[6:7], s[14:15], 0, v[184:185]
	global_load_lds_dwordx4 v[6:7], off
	v_lshl_add_u64 v[6:7], s[14:15], 0, v[144:145]
	s_add_i32 m0, s45, 0x1e000
	s_cmpk_lt_u32 s6, 0x100
	global_load_lds_dwordx4 v[6:7], off
	s_waitcnt vmcnt(8)
	s_barrier
	v_lshlrev_b32_e32 v6, 14, v3
	v_and_b32_e32 v6, 0xffff8000, v6
	v_lshl_add_u32 v4, v4, 11, v6
	v_and_b32_e32 v3, 1, v3
	v_lshl_or_b32 v3, v3, 6, v4
	v_lshl_add_u32 v146, v5, 1, v3
	v_lshlrev_b32_e32 v3, 14, v0
	v_and_b32_e32 v3, 0xffff8000, v3
	s_waitcnt vmcnt(6)
	v_lshl_add_u32 v1, v1, 11, v3
	v_and_b32_e32 v0, 1, v0
	v_or_b32_e32 v154, s7, v16
	v_lshl_or_b32 v0, v0, 6, v1
	v_readlane_b32 s6, v255, 12
	s_cselect_b64 s[14:15], -1, 0
	v_mov_b32_e32 v147, v185
	v_lshl_add_u32 v148, v2, 1, v0
	v_mov_b32_e32 v149, v185
	s_mov_b32 s68, 0
	v_add_u32_e32 v155, 0, v17
	v_readlane_b32 s70, v255, 3
	s_mov_b32 s69, s6
	s_barrier
	v_readlane_b32 s7, v255, 13
	s_branch .LBB0_367

; #define PG8_STAGE(bufoff, gbase, voff) do { _Pragma("unroll") for (int _i = 0; _i < 2; ++_i) \
;         __builtin_amdgcn_global_load_lds((const unsigned*)((const char*)(gbase) + (voff)[_i]), (PG8_LAS unsigned*)(lds + (bufoff) + ldsw + _i * 8192), 16, 0, 0); } while (0)
; #define PG8_WAIT_V(n) asm volatile("s_waitcnt vmcnt(" #n ")" ::: "memory")
; #define PG8_BAR __builtin_amdgcn_s_barrier()
; template <class Epi, class Sched, bool ALIGN_EPI = false, bool SP2 = false>
; __device__ __forceinline__ void gemm_phase(PG8_LAS unsigned char* lds, const Gemm g, const Sched& S, const Epi& E) {
;     ...
;     if constexpr (SP2) {
;         PG8_STAGE(PG8_SB(0, 0), cB, voffB); PG8_STAGE(PG8_SB(0, 1), cB + hstep, voffB); PG8_STAGE(PG8_SA(0, 0), cA, voffA); PG8_STAGE(PG8_SA(0, 1), cA + hstep, voffA);
;         if (wr == 1) PG8_BAR;
;         PG8_WAIT_V(2); PG8_BAR;
;         PG8_STAGE(PG8_SB(1, 0), cB + kstep, voffB); PG8_STAGE(PG8_SA(1, 0), cA + kstep, voffA); PG8_STAGE(PG8_SB(1, 1), cB + hstep + kstep, voffB);
;         PG8_WAIT_V(6); PG8_BAR;
;     } else {
.LBB0_385:
	v_lshrrev_b32_e32 v16, 1, v10
	v_and_b32_e32 v16, 24, v16
	v_and_b32_e32 v11, 15, v10
	v_lshlrev_b32_e32 v17, 1, v16
	v_lshlrev_b32_e32 v10, 2, v10
	s_lshl_b32 s7, s7, 5
	v_lshl_or_b32 v223, s10, 6, v11
	v_lshl_or_b32 v11, v11, 6, v17
	s_lshl_b32 s10, s10, 13
	v_and_b32_e32 v10, 32, v10
	s_and_b32 s7, s7, 0x60
	v_bitop3_b32 v17, v11, s10, v10 bitop3:0xde
	s_lshl_b32 s10, s7, 7
	v_readlane_b32 s22, v255, 14
	v_bitop3_b32 v224, v11, s10, v10 bitop3:0xde
	s_and_b64 s[10:11], s[94:95], exec
	v_readlane_b32 s23, v255, 15
	s_cselect_b32 s11, s65, s35
	s_cselect_b32 s10, s64, s34
	s_add_i32 m0, s43, 0x18000
	v_lshl_add_u64 v[0:1], v[0:1], 0, s[30:31]
	v_lshl_add_u64 v[12:13], s[22:23], 0, v[184:185]
	global_load_lds_dwordx4 v[0:1], off
	v_lshl_add_u64 v[0:1], v[2:3], 0, s[30:31]
	s_add_i32 m0, s43, 0x1a000
	s_add_i32 s47, s43, 0x8000
	s_add_i32 s48, s43, 0xa000
	v_lshl_add_u64 v[14:15], s[22:23], 0, v[190:191]
	global_load_lds_dwordx4 v[0:1], off
	v_lshl_add_u64 v[0:1], v[12:13], 0, s[30:31]
	s_mov_b32 m0, s47
	s_add_u32 s12, s24, 0x20080
	global_load_lds_dwordx4 v[0:1], off
	v_lshl_add_u64 v[0:1], v[14:15], 0, s[30:31]
	s_mov_b32 m0, s48
	s_addc_u32 s13, s25, 0
	global_load_lds_dwordx4 v[0:1], off
	s_add_i32 m0, s43, 0x1c000
	v_lshl_add_u64 v[0:1], s[12:13], 0, v[184:185]
	global_load_lds_dwordx4 v[0:1], off
	v_lshl_add_u64 v[0:1], s[12:13], 0, v[190:191]
	s_add_i32 m0, s43, 0x1e000
	s_cmpk_lt_u32 s6, 0x100
	global_load_lds_dwordx4 v[0:1], off
	s_waitcnt vmcnt(8)
	s_barrier
	v_lshlrev_b32_e32 v0, 13, v7
	v_and_b32_e32 v0, 0xffffc000, v0
	v_lshl_add_u32 v0, v8, 10, v0
	v_and_b32_e32 v1, 1, v7
	v_lshl_or_b32 v0, v1, 6, v0
	v_lshl_add_u32 v192, v9, 1, v0
	v_lshlrev_b32_e32 v0, 13, v4
	v_and_b32_e32 v0, 0xffffc000, v0
	s_waitcnt vmcnt(6)
	v_lshl_add_u32 v0, v5, 10, v0
	v_and_b32_e32 v1, 1, v4
	v_or_b32_e32 v225, s7, v16
	v_lshl_or_b32 v0, v1, 6, v0
	v_readlane_b32 s6, v255, 12
	s_cselect_b64 s[12:13], -1, 0
	v_or_b32_e32 v226, 0xfffff800, v225
	v_add_u32_e32 v227, 0xfffec000, v223
	v_mov_b32_e32 v193, v185
	v_lshl_add_u32 v194, v6, 1, v0
	v_mov_b32_e32 v195, v185
	s_mov_b32 s49, 0
	v_add_u32_e32 v228, 0, v17
	v_readlane_b32 s60, v255, 3
	s_mov_b32 s68, s6
	s_barrier
	v_readlane_b32 s7, v255, 13
	s_branch .LBB0_388

; #define PG8_STAGE(bufoff, gbase, voff) do { _Pragma("unroll") for (int _i = 0; _i < 2; ++_i) \
;         __builtin_amdgcn_global_load_lds((const unsigned*)((const char*)(gbase) + (voff)[_i]), (PG8_LAS unsigned*)(lds + (bufoff) + ldsw + _i * 8192), 16, 0, 0); } while (0)
; #define PG8_WAIT_V(n) asm volatile("s_waitcnt vmcnt(" #n ")" ::: "memory")
; #define PG8_BAR __builtin_amdgcn_s_barrier()
; template <class Epi, class Sched, bool ALIGN_EPI = false, bool SP2 = false>
; __device__ __forceinline__ void gemm_phase(PG8_LAS unsigned char* lds, const Gemm g, const Sched& S, const Epi& E) {
;     ...
;     if constexpr (SP2) {
;         PG8_STAGE(PG8_SB(0, 0), cB, voffB); PG8_STAGE(PG8_SB(0, 1), cB + hstep, voffB); PG8_STAGE(PG8_SA(0, 0), cA, voffA); PG8_STAGE(PG8_SA(0, 1), cA + hstep, voffA);
;         if (wr == 1) PG8_BAR;
;         PG8_WAIT_V(2); PG8_BAR;
;         PG8_STAGE(PG8_SB(1, 0), cB + kstep, voffB); PG8_STAGE(PG8_SA(1, 0), cA + kstep, voffA); PG8_STAGE(PG8_SB(1, 1), cB + hstep + kstep, voffB);
;         PG8_WAIT_V(6); PG8_BAR;
;     } else {
.LBB0_446:
	s_and_b64 s[8:9], s[94:95], exec
	v_readlane_b32 s8, v254, 25
	v_readlane_b32 s10, v254, 27
	v_readlane_b32 s11, v254, 28
	v_readlane_b32 s10, v255, 44
	v_readlane_b32 s11, v255, 45
	v_readlane_b32 s9, v254, 26
	s_mul_i32 s11, s10, 0xc000
	v_readlane_b32 s12, v254, 29
	s_cselect_b32 s9, s9, s65
	s_cselect_b32 s8, s8, s64
	s_add_u32 s11, s66, s11
	s_addc_u32 s12, s67, 0
	v_lshrrev_b32_e32 v16, 1, v10
	s_add_u32 s45, s11, 0x2000
	v_and_b32_e32 v16, 24, v16
	v_readlane_b32 s70, v255, 18
	s_addc_u32 s46, s12, 0
	v_and_b32_e32 v11, 15, v10
	v_lshlrev_b32_e32 v17, 1, v16
	v_lshlrev_b32_e32 v10, 2, v10
	s_lshl_b32 s5, s5, 5
	v_readlane_b32 s71, v255, 19
	v_lshl_or_b32 v157, s24, 6, v11
	v_lshl_or_b32 v11, v11, 6, v17
	s_lshl_b32 s10, s24, 13
	v_and_b32_e32 v10, 32, v10
	s_and_b32 s5, s5, 0x60
	s_add_i32 m0, s37, 0x18000
	v_lshl_add_u64 v[0:1], v[0:1], 0, s[30:31]
	v_lshl_add_u64 v[12:13], s[70:71], 0, v[184:185]
	v_bitop3_b32 v17, v11, s10, v10 bitop3:0xde
	s_lshl_b32 s10, s5, 7
	global_load_lds_dwordx4 v[0:1], off
	v_lshl_add_u64 v[0:1], v[2:3], 0, s[30:31]
	s_add_i32 m0, s37, 0x1a000
	s_add_i32 s47, s37, 0x8000
	s_add_i32 s48, s37, 0xa000
	v_lshl_add_u64 v[14:15], s[70:71], 0, v[144:145]
	v_bitop3_b32 v158, v11, s10, v10 bitop3:0xde
	global_load_lds_dwordx4 v[0:1], off
	v_lshl_add_u64 v[0:1], v[12:13], 0, s[30:31]
	s_mov_b32 m0, s47
	s_add_u32 s10, s72, 0x40080
	global_load_lds_dwordx4 v[0:1], off
	v_lshl_add_u64 v[0:1], v[14:15], 0, s[30:31]
	s_mov_b32 m0, s48
	s_addc_u32 s11, s73, 0
	global_load_lds_dwordx4 v[0:1], off
	s_add_i32 m0, s37, 0x1c000
	v_lshl_add_u64 v[0:1], s[10:11], 0, v[184:185]
	global_load_lds_dwordx4 v[0:1], off
	v_lshl_add_u64 v[0:1], s[10:11], 0, v[144:145]
	s_add_i32 m0, s37, 0x1e000
	v_readlane_b32 s20, v254, 37
	global_load_lds_dwordx4 v[0:1], off
	s_waitcnt vmcnt(8)
	s_barrier
	v_lshlrev_b32_e32 v0, 14, v7
	v_and_b32_e32 v0, 0xffff8000, v0
	v_lshl_add_u32 v0, v8, 11, v0
	v_and_b32_e32 v1, 1, v7
	v_lshl_or_b32 v0, v1, 6, v0
	v_lshl_add_u32 v146, v9, 1, v0
	v_lshlrev_b32_e32 v0, 14, v4
	v_and_b32_e32 v0, 0xffff8000, v0
	s_waitcnt vmcnt(6)
	v_lshl_add_u32 v0, v5, 11, v0
	v_and_b32_e32 v1, 1, v4
	v_readlane_b32 s21, v254, 38
	s_cmpk_lt_u32 s4, 0x100
	v_or_b32_e32 v159, s5, v16
	v_lshl_or_b32 v0, v1, 6, v0
	v_readlane_b32 s4, v255, 12
	v_readlane_b32 s14, v254, 31
	s_cselect_b64 s[10:11], -1, 0
	v_mov_b32_e32 v147, v185
	v_lshl_add_u32 v148, v6, 1, v0
	v_mov_b32_e32 v149, v185
	s_mov_b32 s49, 0
	v_add_u32_e32 v160, 0, v17
	v_readlane_b32 s68, v255, 3
	s_mov_b32 s60, s4
	s_mov_b64 s[20:21], s[70:71]
	v_readlane_b32 s13, v254, 30
	v_readlane_b32 s15, v254, 32
	v_readlane_b32 s16, v254, 33
	v_readlane_b32 s17, v254, 34
	v_readlane_b32 s18, v254, 35
	v_readlane_b32 s19, v254, 36
	v_readlane_b32 s22, v254, 39
	v_readlane_b32 s23, v254, 40
	s_barrier
	v_readlane_b32 s5, v255, 13
	s_branch .LBB0_449
